# resid-GEMM epilogue: second row-half's residual loads issued together with the first half's (spare VGPRs), copies instead of late loads; on top of xattn+mixing edits
# baseline (speedup 1.0000x reference)
.LBB0_184:
	v_and_b32_e32 v133, 64, v216
	v_xor_b32_e32 v132, 16, v216
	v_add_u32_e32 v133, 64, v133
	v_cmp_lt_i32_e32 vcc, v132, v133
	s_lshl_b32 s17, s17, 8
	v_lshl_or_b32 v170, s16, 8, v192
	v_cndmask_b32_e32 v132, v216, v132, vcc
	v_add_u32_e32 v172, s17, v3
	v_ashrrev_i32_e32 v171, 31, v170
	v_lshlrev_b32_e32 v195, 2, v132
	v_xor_b32_e32 v132, 32, v216
	v_cmp_lt_i32_e32 vcc, v132, v133
	v_lshlrev_b64 v[182:183], 1, v[170:171]
	v_ashrrev_i32_e32 v173, 31, v172
	v_cndmask_b32_e32 v132, v216, v132, vcc
	v_lshl_add_u64 v[174:175], s[42:43], 0, v[182:183]
	v_lshlrev_b64 v[184:185], 11, v[172:173]
	v_lshlrev_b32_e32 v180, 2, v132
	v_lshl_add_u64 v[132:133], v[174:175], 0, v[184:185]
	global_load_dwordx4 v[196:199], v[132:133], off
	global_load_dwordx4 v[156:159], v[132:133], off offset:256
	v_or_b32_e32 v132, 16, v172
	v_ashrrev_i32_e32 v133, 31, v132
	v_lshlrev_b64 v[190:191], 11, v[132:133]
	v_lshl_add_u64 v[132:133], v[174:175], 0, v[190:191]
	global_load_dwordx4 v[152:155], v[132:133], off
	global_load_dwordx4 v[148:151], v[132:133], off offset:256
	v_or_b32_e32 v132, 32, v172
	v_ashrrev_i32_e32 v133, 31, v132
	v_lshlrev_b64 v[178:179], 11, v[132:133]
	v_lshl_add_u64 v[132:133], v[174:175], 0, v[178:179]
	global_load_dwordx4 v[144:147], v[132:133], off
	global_load_dwordx4 v[140:143], v[132:133], off offset:256
	v_or_b32_e32 v132, 48, v172
	v_ashrrev_i32_e32 v133, 31, v132
	v_lshlrev_b64 v[176:177], 11, v[132:133]
	v_lshl_add_u64 v[132:133], v[174:175], 0, v[176:177]
	global_load_dwordx4 v[136:139], v[132:133], off
	s_nop 0
	global_load_dwordx4 v[132:135], v[132:133], off offset:256
	v_lshlrev_b64 v[160:161], 11, v[172:173]
	v_lshl_add_u64 v[160:161], v[174:175], 0, v[160:161]
	s_mov_b64 s[100:101], 0x40000
	v_lshl_add_u64 v[162:163], v[160:161], 0, s[100:101]
	global_load_dwordx4 v[204:207], v[162:163], off
	global_load_dwordx4 v[208:211], v[162:163], off offset:256
	s_mov_b64 s[100:101], 0x48000
	v_lshl_add_u64 v[162:163], v[160:161], 0, s[100:101]
	global_load_dwordx4 v[224:227], v[162:163], off
	global_load_dwordx4 v[228:231], v[162:163], off offset:256
	s_mov_b64 s[100:101], 0x50000
	v_lshl_add_u64 v[162:163], v[160:161], 0, s[100:101]
	global_load_dwordx4 v[232:235], v[162:163], off
	global_load_dwordx4 v[236:239], v[162:163], off offset:256
	s_mov_b64 s[100:101], 0x58000
	v_lshl_add_u64 v[162:163], v[160:161], 0, s[100:101]
	global_load_dwordx4 v[240:243], v[162:163], off
	global_load_dwordx4 v[218:221], v[162:163], off offset:256
	s_waitcnt vmcnt(8)
	v_lshlrev_b32_e32 v200, 16, v196
	v_and_b32_e32 v201, 0xffff0000, v196
	v_lshlrev_b32_e32 v196, 16, v197
	v_and_b32_e32 v197, 0xffff0000, v197
	v_lshlrev_b32_e32 v202, 16, v198
	v_and_b32_e32 v203, 0xffff0000, v198
	v_lshlrev_b32_e32 v198, 16, v199
	v_and_b32_e32 v199, 0xffff0000, v199
	v_pk_add_f32 v[130:131], v[130:131], v[196:197]
	v_pk_add_f32 v[128:129], v[128:129], v[200:201]
	v_pk_add_f32 v[196:197], v[126:127], v[198:199]
	v_mul_f32_e32 v126, v129, v129
	v_mul_f32_e32 v127, v131, v131
	v_pk_add_f32 v[124:125], v[124:125], v[202:203]
	v_fmac_f32_e32 v126, v128, v128
	v_fmac_f32_e32 v127, v130, v130
	v_add_f32_e32 v126, v126, v127
	v_mul_f32_e32 v127, v125, v125
	v_fmac_f32_e32 v127, v124, v124
	v_add_f32_e32 v126, v127, v126
	v_mul_f32_e32 v127, v197, v197
	v_fmac_f32_e32 v127, v196, v196
	v_add_f32_e32 v198, v127, v126
	v_cvt_pk_bf16_f32 v126, v128, v129
	v_cvt_pk_bf16_f32 v128, v124, v125
	v_lshl_add_u64 v[124:125], s[42:43], 0, v[184:185]
	v_cvt_pk_bf16_f32 v127, v130, v131
	v_cvt_pk_bf16_f32 v129, v196, v197
	v_lshl_add_u64 v[124:125], v[124:125], 0, v[182:183]
	global_store_dwordx4 v[124:125], v[126:129], off
	v_lshlrev_b32_e32 v130, 16, v158
	v_and_b32_e32 v131, 0xffff0000, v158
	v_lshlrev_b32_e32 v126, 16, v156
	v_and_b32_e32 v127, 0xffff0000, v156
	v_lshlrev_b32_e32 v128, 16, v157
	v_and_b32_e32 v129, 0xffff0000, v157
	v_lshlrev_b32_e32 v156, 16, v159
	v_and_b32_e32 v157, 0xffff0000, v159
	v_pk_add_f32 v[122:123], v[122:123], v[128:129]
	v_pk_add_f32 v[120:121], v[120:121], v[126:127]
	v_pk_add_f32 v[126:127], v[118:119], v[156:157]
	v_pk_add_f32 v[118:119], v[116:117], v[130:131]
	v_mul_f32_e32 v116, v121, v121
	v_mul_f32_e32 v117, v123, v123
	v_fmac_f32_e32 v116, v120, v120
	v_fmac_f32_e32 v117, v122, v122
	v_add_f32_e32 v116, v116, v117
	v_mul_f32_e32 v117, v119, v119
	v_fmac_f32_e32 v117, v118, v118
	v_add_f32_e32 v116, v117, v116
	v_mul_f32_e32 v117, v127, v127
	v_fmac_f32_e32 v117, v126, v126
	v_add_f32_e32 v116, v117, v116
	v_add_f32_e32 v128, v198, v116
	v_cvt_pk_bf16_f32 v116, v120, v121
	v_cvt_pk_bf16_f32 v117, v122, v123
	v_cvt_pk_bf16_f32 v118, v118, v119
	v_cvt_pk_bf16_f32 v119, v126, v127
	global_store_dwordx4 v[124:125], v[116:119], off offset:256
	ds_bpermute_b32 v116, v195, v128
	s_waitcnt lgkmcnt(0)
	v_add_f32_e32 v116, v128, v116
	ds_bpermute_b32 v117, v180, v116
	s_and_saveexec_b64 s[10:11], s[6:7]
	s_cbranch_execz .LBB0_186
	s_waitcnt lgkmcnt(0)
	v_add_f32_e32 v116, v116, v117
	ds_write_b32 v193, v116

.LBB0_192:
	s_or_b64 exec, exec, s[10:11]
	s_waitcnt lgkmcnt(0)
	v_lshlrev_b64 v[68:69], 11, v[172:173]
	s_mov_b64 s[10:11], 0x40000
	v_lshl_add_u64 v[106:107], v[68:69], 0, s[10:11]
	v_lshl_add_u64 v[70:71], v[174:175], 0, v[106:107]
	s_mov_b64 s[10:11], 0x48000
	v_lshl_add_u64 v[96:97], v[68:69], 0, s[10:11]
	s_mov_b64 s[10:11], 0x50000
	v_lshl_add_u64 v[94:95], v[68:69], 0, s[10:11]
	s_mov_b64 s[10:11], 0x58000
	v_lshl_add_u64 v[70:71], v[174:175], 0, v[96:97]
	v_lshl_add_u64 v[92:93], v[68:69], 0, s[10:11]
	v_lshl_add_u64 v[70:71], v[174:175], 0, v[94:95]
	v_lshl_add_u64 v[68:69], v[174:175], 0, v[92:93]
	s_waitcnt vmcnt(8)
	v_mov_b32_e32 v98, v204
	v_mov_b32_e32 v99, v205
	v_mov_b32_e32 v100, v206
	v_mov_b32_e32 v101, v207
	v_mov_b32_e32 v102, v208
	v_mov_b32_e32 v103, v209
	v_mov_b32_e32 v104, v210
	v_mov_b32_e32 v105, v211
	v_mov_b32_e32 v88, v224
	v_mov_b32_e32 v89, v225
	v_mov_b32_e32 v90, v226
	v_mov_b32_e32 v91, v227
	v_mov_b32_e32 v84, v228
	v_mov_b32_e32 v85, v229
	v_mov_b32_e32 v86, v230
	v_mov_b32_e32 v87, v231
	v_mov_b32_e32 v80, v232
	v_mov_b32_e32 v81, v233
	v_mov_b32_e32 v82, v234
	v_mov_b32_e32 v83, v235
	v_mov_b32_e32 v76, v236
	v_mov_b32_e32 v77, v237
	v_mov_b32_e32 v78, v238
	v_mov_b32_e32 v79, v239
	v_mov_b32_e32 v72, v240
	v_mov_b32_e32 v73, v241
	v_mov_b32_e32 v74, v242
	v_mov_b32_e32 v75, v243
	v_mov_b32_e32 v68, v218
	v_mov_b32_e32 v69, v219
	v_mov_b32_e32 v70, v220
	v_mov_b32_e32 v71, v221
	v_lshlrev_b32_e32 v108, 16, v98
	v_and_b32_e32 v109, 0xffff0000, v98
	v_lshlrev_b32_e32 v98, 16, v99
	v_and_b32_e32 v99, 0xffff0000, v99
	v_lshlrev_b32_e32 v110, 16, v100
	v_and_b32_e32 v111, 0xffff0000, v100
	v_lshlrev_b32_e32 v100, 16, v101
	v_and_b32_e32 v101, 0xffff0000, v101
	v_pk_add_f32 v[66:67], v[66:67], v[98:99]
	v_pk_add_f32 v[64:65], v[64:65], v[108:109]
	v_pk_add_f32 v[98:99], v[62:63], v[100:101]
	v_mul_f32_e32 v62, v65, v65
	v_mul_f32_e32 v63, v67, v67
	v_pk_add_f32 v[60:61], v[60:61], v[110:111]
	v_fmac_f32_e32 v62, v64, v64
	v_fmac_f32_e32 v63, v66, v66
	v_add_f32_e32 v62, v62, v63
	v_mul_f32_e32 v63, v61, v61
	v_fmac_f32_e32 v63, v60, v60
	v_add_f32_e32 v62, v63, v62
	v_mul_f32_e32 v63, v99, v99
	v_fmac_f32_e32 v63, v98, v98
	v_add_f32_e32 v100, v63, v62
	v_cvt_pk_bf16_f32 v62, v64, v65
	v_cvt_pk_bf16_f32 v64, v60, v61
	v_lshl_add_u64 v[60:61], s[42:43], 0, v[106:107]
	v_cvt_pk_bf16_f32 v63, v66, v67
	v_cvt_pk_bf16_f32 v65, v98, v99
	v_lshl_add_u64 v[60:61], v[170:171], 1, v[60:61]
	global_store_dwordx4 v[60:61], v[62:65], off
	v_lshlrev_b32_e32 v66, 16, v104
	v_and_b32_e32 v67, 0xffff0000, v104
	v_lshlrev_b32_e32 v62, 16, v102
	v_and_b32_e32 v63, 0xffff0000, v102
	v_lshlrev_b32_e32 v64, 16, v103
	v_and_b32_e32 v65, 0xffff0000, v103
	v_lshlrev_b32_e32 v98, 16, v105
	v_and_b32_e32 v99, 0xffff0000, v105
	v_pk_add_f32 v[58:59], v[58:59], v[64:65]
	v_pk_add_f32 v[56:57], v[56:57], v[62:63]
	v_pk_add_f32 v[62:63], v[54:55], v[98:99]
	v_pk_add_f32 v[54:55], v[52:53], v[66:67]
	v_mul_f32_e32 v52, v57, v57
	v_mul_f32_e32 v53, v59, v59
	v_fmac_f32_e32 v52, v56, v56
	v_fmac_f32_e32 v53, v58, v58
	v_add_f32_e32 v52, v52, v53
	v_mul_f32_e32 v53, v55, v55
	v_fmac_f32_e32 v53, v54, v54
	v_add_f32_e32 v52, v53, v52
	v_mul_f32_e32 v53, v63, v63
	v_fmac_f32_e32 v53, v62, v62
	v_add_f32_e32 v52, v53, v52
	v_add_f32_e32 v64, v100, v52
	v_cvt_pk_bf16_f32 v52, v56, v57
	v_cvt_pk_bf16_f32 v53, v58, v59
	v_cvt_pk_bf16_f32 v54, v54, v55
	v_cvt_pk_bf16_f32 v55, v62, v63
	global_store_dwordx4 v[60:61], v[52:55], off offset:256
	ds_bpermute_b32 v52, v195, v64
	s_waitcnt lgkmcnt(0)
	v_add_f32_e32 v52, v64, v52
	ds_bpermute_b32 v53, v180, v52
	s_and_saveexec_b64 s[10:11], s[6:7]
	s_cbranch_execz .LBB0_194
	s_waitcnt lgkmcnt(0)
	v_add_f32_e32 v52, v52, v53
	ds_write_b32 v193, v52 offset:2048
.LBB0_194:
	s_or_b64 exec, exec, s[10:11]
	v_lshlrev_b32_e32 v52, 16, v88
	s_waitcnt lgkmcnt(0)
	v_and_b32_e32 v53, 0xffff0000, v88
	v_lshlrev_b32_e32 v54, 16, v89
	v_and_b32_e32 v55, 0xffff0000, v89
	v_lshlrev_b32_e32 v56, 16, v90
	v_and_b32_e32 v57, 0xffff0000, v90
	v_lshlrev_b32_e32 v58, 16, v91
	v_and_b32_e32 v59, 0xffff0000, v91
	v_pk_add_f32 v[50:51], v[50:51], v[54:55]
	v_pk_add_f32 v[48:49], v[48:49], v[52:53]
	v_pk_add_f32 v[52:53], v[46:47], v[58:59]
	v_pk_add_f32 v[46:47], v[44:45], v[56:57]
	v_mul_f32_e32 v44, v49, v49
	v_mul_f32_e32 v45, v51, v51
	v_fmac_f32_e32 v44, v48, v48
	v_fmac_f32_e32 v45, v50, v50
	v_add_f32_e32 v44, v44, v45
	v_mul_f32_e32 v45, v47, v47
	v_fmac_f32_e32 v45, v46, v46
	v_add_f32_e32 v44, v45, v44
	v_mul_f32_e32 v45, v53, v53
	v_fmac_f32_e32 v45, v52, v52
	v_add_f32_e32 v56, v45, v44
	v_cvt_pk_bf16_f32 v44, v48, v49
	v_cvt_pk_bf16_f32 v45, v50, v51
	v_lshlrev_b32_e32 v48, 16, v84
	v_and_b32_e32 v49, 0xffff0000, v84
	v_lshlrev_b32_e32 v50, 16, v85
	v_and_b32_e32 v51, 0xffff0000, v85
	v_cvt_pk_bf16_f32 v46, v46, v47
	v_cvt_pk_bf16_f32 v47, v52, v53
	v_lshlrev_b32_e32 v52, 16, v86
	v_and_b32_e32 v53, 0xffff0000, v86
	v_pk_add_f32 v[42:43], v[42:43], v[50:51]
	v_pk_add_f32 v[40:41], v[40:41], v[48:49]
	v_pk_add_f32 v[50:51], v[36:37], v[52:53]
	v_mul_f32_e32 v36, v41, v41
	v_mul_f32_e32 v37, v43, v43
	v_fmac_f32_e32 v36, v40, v40
	v_fmac_f32_e32 v37, v42, v42
	v_lshlrev_b32_e32 v54, 16, v87
	v_and_b32_e32 v55, 0xffff0000, v87
	v_add_f32_e32 v36, v36, v37
	v_mul_f32_e32 v37, v51, v51
	v_pk_add_f32 v[48:49], v[38:39], v[54:55]
	v_fmac_f32_e32 v37, v50, v50
	v_add_f32_e32 v36, v37, v36
	v_mul_f32_e32 v37, v49, v49
	v_fmac_f32_e32 v37, v48, v48
	v_add_f32_e32 v36, v37, v36
	v_add_f32_e32 v39, v56, v36
	ds_bpermute_b32 v54, v195, v39
	v_lshl_add_u64 v[36:37], s[42:43], 0, v[96:97]
	v_lshl_add_u64 v[52:53], v[170:171], 1, v[36:37]
	v_cvt_pk_bf16_f32 v38, v40, v41
	v_cvt_pk_bf16_f32 v40, v50, v51
	s_waitcnt lgkmcnt(0)
	v_add_f32_e32 v36, v39, v54
	ds_bpermute_b32 v37, v180, v36
	v_cvt_pk_bf16_f32 v39, v42, v43
	v_cvt_pk_bf16_f32 v41, v48, v49
	global_store_dwordx4 v[52:53], v[44:47], off
	global_store_dwordx4 v[52:53], v[38:41], off offset:256
	s_and_saveexec_b64 s[10:11], s[6:7]
	s_cbranch_execz .LBB0_196
	s_waitcnt lgkmcnt(0)
	v_add_f32_e32 v36, v36, v37
	ds_write_b32 v193, v36 offset:2304
.LBB0_196:
	s_or_b64 exec, exec, s[10:11]
	v_lshlrev_b32_e32 v36, 16, v80
	s_waitcnt lgkmcnt(0)
	v_and_b32_e32 v37, 0xffff0000, v80
	v_lshlrev_b32_e32 v38, 16, v81
	v_and_b32_e32 v39, 0xffff0000, v81
	v_lshlrev_b32_e32 v40, 16, v82
	v_and_b32_e32 v41, 0xffff0000, v82
	v_lshlrev_b32_e32 v42, 16, v83
	v_and_b32_e32 v43, 0xffff0000, v83
	v_pk_add_f32 v[34:35], v[34:35], v[38:39]
	v_pk_add_f32 v[32:33], v[32:33], v[36:37]
	v_pk_add_f32 v[36:37], v[30:31], v[42:43]
	v_pk_add_f32 v[30:31], v[28:29], v[40:41]
	v_mul_f32_e32 v28, v33, v33
	v_mul_f32_e32 v29, v35, v35
	v_fmac_f32_e32 v28, v32, v32
	v_fmac_f32_e32 v29, v34, v34
	v_add_f32_e32 v28, v28, v29
	v_mul_f32_e32 v29, v31, v31
	v_fmac_f32_e32 v29, v30, v30
	v_add_f32_e32 v28, v29, v28
	v_mul_f32_e32 v29, v37, v37
	v_fmac_f32_e32 v29, v36, v36
	v_add_f32_e32 v40, v29, v28
	v_cvt_pk_bf16_f32 v28, v32, v33
	v_cvt_pk_bf16_f32 v29, v34, v35
	v_lshlrev_b32_e32 v32, 16, v76
	v_and_b32_e32 v33, 0xffff0000, v76
	v_lshlrev_b32_e32 v34, 16, v77
	v_and_b32_e32 v35, 0xffff0000, v77
	v_cvt_pk_bf16_f32 v30, v30, v31
	v_cvt_pk_bf16_f32 v31, v36, v37
	v_lshlrev_b32_e32 v36, 16, v78
	v_and_b32_e32 v37, 0xffff0000, v78
	v_pk_add_f32 v[26:27], v[26:27], v[34:35]
	v_pk_add_f32 v[24:25], v[24:25], v[32:33]
	v_pk_add_f32 v[34:35], v[20:21], v[36:37]
	v_mul_f32_e32 v20, v25, v25
	v_mul_f32_e32 v21, v27, v27
	v_fmac_f32_e32 v20, v24, v24
	v_fmac_f32_e32 v21, v26, v26
	v_lshlrev_b32_e32 v38, 16, v79
	v_and_b32_e32 v39, 0xffff0000, v79
	v_add_f32_e32 v20, v20, v21
	v_mul_f32_e32 v21, v35, v35
	v_pk_add_f32 v[32:33], v[22:23], v[38:39]
	v_fmac_f32_e32 v21, v34, v34
	v_add_f32_e32 v20, v21, v20
	v_mul_f32_e32 v21, v33, v33
	v_fmac_f32_e32 v21, v32, v32
	v_add_f32_e32 v20, v21, v20
	v_add_f32_e32 v23, v40, v20
	ds_bpermute_b32 v38, v195, v23
	v_lshl_add_u64 v[20:21], s[42:43], 0, v[94:95]
	v_lshl_add_u64 v[36:37], v[170:171], 1, v[20:21]
	v_cvt_pk_bf16_f32 v22, v24, v25
	v_cvt_pk_bf16_f32 v24, v34, v35
	s_waitcnt lgkmcnt(0)
	v_add_f32_e32 v20, v23, v38
	ds_bpermute_b32 v21, v180, v20
	v_cvt_pk_bf16_f32 v23, v26, v27
	v_cvt_pk_bf16_f32 v25, v32, v33
	global_store_dwordx4 v[36:37], v[28:31], off
	global_store_dwordx4 v[36:37], v[22:25], off offset:256
	s_and_saveexec_b64 s[10:11], s[6:7]
	s_cbranch_execz .LBB0_198
	s_waitcnt lgkmcnt(0)
	v_add_f32_e32 v20, v20, v21
	ds_write_b32 v193, v20 offset:2560
.LBB0_198:
	s_or_b64 exec, exec, s[10:11]
	v_lshlrev_b32_e32 v20, 16, v72
	s_waitcnt lgkmcnt(0)
	v_and_b32_e32 v21, 0xffff0000, v72
	v_lshlrev_b32_e32 v22, 16, v73
	v_and_b32_e32 v23, 0xffff0000, v73
	v_lshlrev_b32_e32 v24, 16, v74
	v_and_b32_e32 v25, 0xffff0000, v74
	v_lshlrev_b32_e32 v26, 16, v75
	v_and_b32_e32 v27, 0xffff0000, v75
	v_pk_add_f32 v[18:19], v[18:19], v[22:23]
	v_pk_add_f32 v[16:17], v[16:17], v[20:21]
	v_pk_add_f32 v[20:21], v[14:15], v[26:27]
	v_pk_add_f32 v[14:15], v[12:13], v[24:25]
	v_mul_f32_e32 v12, v17, v17
	v_mul_f32_e32 v13, v19, v19
	v_fmac_f32_e32 v12, v16, v16
	v_fmac_f32_e32 v13, v18, v18
	v_add_f32_e32 v12, v12, v13
	v_mul_f32_e32 v13, v15, v15
	v_fmac_f32_e32 v13, v14, v14
	v_add_f32_e32 v12, v13, v12
	v_mul_f32_e32 v13, v21, v21
	v_fmac_f32_e32 v13, v20, v20
	v_add_f32_e32 v24, v13, v12
	v_cvt_pk_bf16_f32 v12, v16, v17
	v_cvt_pk_bf16_f32 v13, v18, v19
	v_lshlrev_b32_e32 v16, 16, v68
	v_and_b32_e32 v17, 0xffff0000, v68
	v_lshlrev_b32_e32 v18, 16, v69
	v_and_b32_e32 v19, 0xffff0000, v69
	v_cvt_pk_bf16_f32 v14, v14, v15
	v_cvt_pk_bf16_f32 v15, v20, v21
	v_lshlrev_b32_e32 v20, 16, v70
	v_and_b32_e32 v21, 0xffff0000, v70
	v_pk_add_f32 v[10:11], v[10:11], v[18:19]
	v_pk_add_f32 v[8:9], v[8:9], v[16:17]
	v_pk_add_f32 v[18:19], v[4:5], v[20:21]
	v_mul_f32_e32 v4, v9, v9
	v_mul_f32_e32 v5, v11, v11
	v_fmac_f32_e32 v4, v8, v8
	v_fmac_f32_e32 v5, v10, v10
	v_lshlrev_b32_e32 v22, 16, v71
	v_and_b32_e32 v23, 0xffff0000, v71
	v_add_f32_e32 v4, v4, v5
	v_mul_f32_e32 v5, v19, v19
	v_pk_add_f32 v[16:17], v[6:7], v[22:23]
	v_fmac_f32_e32 v5, v18, v18
	v_add_f32_e32 v4, v5, v4
	v_mul_f32_e32 v5, v17, v17
	v_fmac_f32_e32 v5, v16, v16
	v_add_f32_e32 v4, v5, v4
	v_add_f32_e32 v7, v24, v4
	ds_bpermute_b32 v22, v195, v7
	v_lshl_add_u64 v[4:5], s[42:43], 0, v[92:93]
	v_lshl_add_u64 v[20:21], v[170:171], 1, v[4:5]
	v_cvt_pk_bf16_f32 v6, v8, v9
	v_cvt_pk_bf16_f32 v8, v18, v19
	s_waitcnt lgkmcnt(0)
	v_add_f32_e32 v4, v7, v22
	ds_bpermute_b32 v5, v180, v4
	v_cvt_pk_bf16_f32 v7, v10, v11
	v_cvt_pk_bf16_f32 v9, v16, v17
	global_store_dwordx4 v[20:21], v[12:15], off
	global_store_dwordx4 v[20:21], v[6:9], off offset:256
	s_and_saveexec_b64 s[10:11], s[6:7]
	s_cbranch_execz .LBB0_200
	s_waitcnt lgkmcnt(0)
	v_add_f32_e32 v4, v4, v5
	ds_write_b32 v193, v4 offset:2816

.LBB0_337:
	v_and_b32_e32 v133, 64, v216
	v_xor_b32_e32 v132, 16, v216
	v_add_u32_e32 v133, 64, v133
	v_cmp_lt_i32_e32 vcc, v132, v133
	s_lshl_b32 s15, s15, 8
	v_lshl_or_b32 v170, s14, 8, v192
	v_cndmask_b32_e32 v132, v216, v132, vcc
	v_add_u32_e32 v172, s15, v3
	v_ashrrev_i32_e32 v171, 31, v170
	v_lshlrev_b32_e32 v195, 2, v132
	v_xor_b32_e32 v132, 32, v216
	v_cmp_lt_i32_e32 vcc, v132, v133
	v_lshlrev_b64 v[182:183], 1, v[170:171]
	v_ashrrev_i32_e32 v173, 31, v172
	v_cndmask_b32_e32 v132, v216, v132, vcc
	v_lshl_add_u64 v[174:175], s[42:43], 0, v[182:183]
	v_lshlrev_b64 v[184:185], 11, v[172:173]
	v_lshlrev_b32_e32 v180, 2, v132
	v_lshl_add_u64 v[132:133], v[174:175], 0, v[184:185]
	global_load_dwordx4 v[196:199], v[132:133], off
	global_load_dwordx4 v[156:159], v[132:133], off offset:256
	v_or_b32_e32 v132, 16, v172
	v_ashrrev_i32_e32 v133, 31, v132
	v_lshlrev_b64 v[190:191], 11, v[132:133]
	v_lshl_add_u64 v[132:133], v[174:175], 0, v[190:191]
	global_load_dwordx4 v[152:155], v[132:133], off
	global_load_dwordx4 v[148:151], v[132:133], off offset:256
	v_or_b32_e32 v132, 32, v172
	v_ashrrev_i32_e32 v133, 31, v132
	v_lshlrev_b64 v[178:179], 11, v[132:133]
	v_lshl_add_u64 v[132:133], v[174:175], 0, v[178:179]
	global_load_dwordx4 v[144:147], v[132:133], off
	global_load_dwordx4 v[140:143], v[132:133], off offset:256
	v_or_b32_e32 v132, 48, v172
	v_ashrrev_i32_e32 v133, 31, v132
	v_lshlrev_b64 v[176:177], 11, v[132:133]
	v_lshl_add_u64 v[132:133], v[174:175], 0, v[176:177]
	global_load_dwordx4 v[136:139], v[132:133], off
	s_nop 0
	global_load_dwordx4 v[132:135], v[132:133], off offset:256
	v_lshlrev_b64 v[160:161], 11, v[172:173]
	v_lshl_add_u64 v[160:161], v[174:175], 0, v[160:161]
	s_mov_b64 s[100:101], 0x40000
	v_lshl_add_u64 v[162:163], v[160:161], 0, s[100:101]
	global_load_dwordx4 v[204:207], v[162:163], off
	global_load_dwordx4 v[208:211], v[162:163], off offset:256
	s_mov_b64 s[100:101], 0x48000
	v_lshl_add_u64 v[162:163], v[160:161], 0, s[100:101]
	global_load_dwordx4 v[224:227], v[162:163], off
	global_load_dwordx4 v[228:231], v[162:163], off offset:256
	s_mov_b64 s[100:101], 0x50000
	v_lshl_add_u64 v[162:163], v[160:161], 0, s[100:101]
	global_load_dwordx4 v[232:235], v[162:163], off
	global_load_dwordx4 v[236:239], v[162:163], off offset:256
	s_mov_b64 s[100:101], 0x58000
	v_lshl_add_u64 v[162:163], v[160:161], 0, s[100:101]
	global_load_dwordx4 v[240:243], v[162:163], off
	global_load_dwordx4 v[218:221], v[162:163], off offset:256
	s_waitcnt vmcnt(8)
	v_lshlrev_b32_e32 v200, 16, v196
	v_and_b32_e32 v201, 0xffff0000, v196
	v_lshlrev_b32_e32 v196, 16, v197
	v_and_b32_e32 v197, 0xffff0000, v197
	v_lshlrev_b32_e32 v202, 16, v198
	v_and_b32_e32 v203, 0xffff0000, v198
	v_lshlrev_b32_e32 v198, 16, v199
	v_and_b32_e32 v199, 0xffff0000, v199
	v_pk_add_f32 v[130:131], v[130:131], v[196:197]
	v_pk_add_f32 v[128:129], v[128:129], v[200:201]
	v_pk_add_f32 v[196:197], v[126:127], v[198:199]
	v_mul_f32_e32 v126, v129, v129
	v_mul_f32_e32 v127, v131, v131
	v_pk_add_f32 v[124:125], v[124:125], v[202:203]
	v_fmac_f32_e32 v126, v128, v128
	v_fmac_f32_e32 v127, v130, v130
	v_add_f32_e32 v126, v126, v127
	v_mul_f32_e32 v127, v125, v125
	v_fmac_f32_e32 v127, v124, v124
	v_add_f32_e32 v126, v127, v126
	v_mul_f32_e32 v127, v197, v197
	v_fmac_f32_e32 v127, v196, v196
	v_add_f32_e32 v198, v127, v126
	v_cvt_pk_bf16_f32 v126, v128, v129
	v_cvt_pk_bf16_f32 v128, v124, v125
	v_lshl_add_u64 v[124:125], s[42:43], 0, v[184:185]
	v_cvt_pk_bf16_f32 v127, v130, v131
	v_cvt_pk_bf16_f32 v129, v196, v197
	v_lshl_add_u64 v[124:125], v[124:125], 0, v[182:183]
	global_store_dwordx4 v[124:125], v[126:129], off
	v_lshlrev_b32_e32 v130, 16, v158
	v_and_b32_e32 v131, 0xffff0000, v158
	v_lshlrev_b32_e32 v126, 16, v156
	v_and_b32_e32 v127, 0xffff0000, v156
	v_lshlrev_b32_e32 v128, 16, v157
	v_and_b32_e32 v129, 0xffff0000, v157
	v_lshlrev_b32_e32 v156, 16, v159
	v_and_b32_e32 v157, 0xffff0000, v159
	v_pk_add_f32 v[122:123], v[122:123], v[128:129]
	v_pk_add_f32 v[120:121], v[120:121], v[126:127]
	v_pk_add_f32 v[126:127], v[118:119], v[156:157]
	v_pk_add_f32 v[118:119], v[116:117], v[130:131]
	v_mul_f32_e32 v116, v121, v121
	v_mul_f32_e32 v117, v123, v123
	v_fmac_f32_e32 v116, v120, v120
	v_fmac_f32_e32 v117, v122, v122
	v_add_f32_e32 v116, v116, v117
	v_mul_f32_e32 v117, v119, v119
	v_fmac_f32_e32 v117, v118, v118
	v_add_f32_e32 v116, v117, v116
	v_mul_f32_e32 v117, v127, v127
	v_fmac_f32_e32 v117, v126, v126
	v_add_f32_e32 v116, v117, v116
	v_add_f32_e32 v128, v198, v116
	v_cvt_pk_bf16_f32 v116, v120, v121
	v_cvt_pk_bf16_f32 v117, v122, v123
	v_cvt_pk_bf16_f32 v118, v118, v119
	v_cvt_pk_bf16_f32 v119, v126, v127
	global_store_dwordx4 v[124:125], v[116:119], off offset:256
	ds_bpermute_b32 v116, v195, v128
	s_waitcnt lgkmcnt(0)
	v_add_f32_e32 v116, v128, v116
	ds_bpermute_b32 v117, v180, v116
	s_and_saveexec_b64 s[44:45], s[6:7]
	s_cbranch_execz .LBB0_339
	s_waitcnt lgkmcnt(0)
	v_add_f32_e32 v116, v116, v117
	ds_write_b32 v193, v116

.LBB0_345:
	s_or_b64 exec, exec, s[44:45]
	s_waitcnt lgkmcnt(0)
	v_lshlrev_b64 v[68:69], 11, v[172:173]
	s_mov_b64 s[40:41], 0x40000
	v_lshl_add_u64 v[106:107], v[68:69], 0, s[40:41]
	v_lshl_add_u64 v[70:71], v[174:175], 0, v[106:107]
	s_mov_b64 s[40:41], 0x48000
	v_lshl_add_u64 v[96:97], v[68:69], 0, s[40:41]
	s_mov_b64 s[40:41], 0x50000
	v_lshl_add_u64 v[94:95], v[68:69], 0, s[40:41]
	s_mov_b64 s[40:41], 0x58000
	v_lshl_add_u64 v[70:71], v[174:175], 0, v[96:97]
	v_lshl_add_u64 v[92:93], v[68:69], 0, s[40:41]
	v_lshl_add_u64 v[70:71], v[174:175], 0, v[94:95]
	v_lshl_add_u64 v[68:69], v[174:175], 0, v[92:93]
	s_waitcnt vmcnt(8)
	v_mov_b32_e32 v98, v204
	v_mov_b32_e32 v99, v205
	v_mov_b32_e32 v100, v206
	v_mov_b32_e32 v101, v207
	v_mov_b32_e32 v102, v208
	v_mov_b32_e32 v103, v209
	v_mov_b32_e32 v104, v210
	v_mov_b32_e32 v105, v211
	v_mov_b32_e32 v88, v224
	v_mov_b32_e32 v89, v225
	v_mov_b32_e32 v90, v226
	v_mov_b32_e32 v91, v227
	v_mov_b32_e32 v84, v228
	v_mov_b32_e32 v85, v229
	v_mov_b32_e32 v86, v230
	v_mov_b32_e32 v87, v231
	v_mov_b32_e32 v80, v232
	v_mov_b32_e32 v81, v233
	v_mov_b32_e32 v82, v234
	v_mov_b32_e32 v83, v235
	v_mov_b32_e32 v76, v236
	v_mov_b32_e32 v77, v237
	v_mov_b32_e32 v78, v238
	v_mov_b32_e32 v79, v239
	v_mov_b32_e32 v72, v240
	v_mov_b32_e32 v73, v241
	v_mov_b32_e32 v74, v242
	v_mov_b32_e32 v75, v243
	v_mov_b32_e32 v68, v218
	v_mov_b32_e32 v69, v219
	v_mov_b32_e32 v70, v220
	v_mov_b32_e32 v71, v221
	v_lshlrev_b32_e32 v108, 16, v98
	v_and_b32_e32 v109, 0xffff0000, v98
	v_lshlrev_b32_e32 v98, 16, v99
	v_and_b32_e32 v99, 0xffff0000, v99
	v_lshlrev_b32_e32 v110, 16, v100
	v_and_b32_e32 v111, 0xffff0000, v100
	v_lshlrev_b32_e32 v100, 16, v101
	v_and_b32_e32 v101, 0xffff0000, v101
	v_pk_add_f32 v[66:67], v[66:67], v[98:99]
	v_pk_add_f32 v[64:65], v[64:65], v[108:109]
	v_pk_add_f32 v[98:99], v[62:63], v[100:101]
	v_mul_f32_e32 v62, v65, v65
	v_mul_f32_e32 v63, v67, v67
	v_pk_add_f32 v[60:61], v[60:61], v[110:111]
	v_fmac_f32_e32 v62, v64, v64
	v_fmac_f32_e32 v63, v66, v66
	v_add_f32_e32 v62, v62, v63
	v_mul_f32_e32 v63, v61, v61
	v_fmac_f32_e32 v63, v60, v60
	v_add_f32_e32 v62, v63, v62
	v_mul_f32_e32 v63, v99, v99
	v_fmac_f32_e32 v63, v98, v98
	v_add_f32_e32 v100, v63, v62
	v_cvt_pk_bf16_f32 v62, v64, v65
	v_cvt_pk_bf16_f32 v64, v60, v61
	v_lshl_add_u64 v[60:61], s[42:43], 0, v[106:107]
	v_cvt_pk_bf16_f32 v63, v66, v67
	v_cvt_pk_bf16_f32 v65, v98, v99
	v_lshl_add_u64 v[60:61], v[170:171], 1, v[60:61]
	global_store_dwordx4 v[60:61], v[62:65], off
	v_lshlrev_b32_e32 v66, 16, v104
	v_and_b32_e32 v67, 0xffff0000, v104
	v_lshlrev_b32_e32 v62, 16, v102
	v_and_b32_e32 v63, 0xffff0000, v102
	v_lshlrev_b32_e32 v64, 16, v103
	v_and_b32_e32 v65, 0xffff0000, v103
	v_lshlrev_b32_e32 v98, 16, v105
	v_and_b32_e32 v99, 0xffff0000, v105
	v_pk_add_f32 v[58:59], v[58:59], v[64:65]
	v_pk_add_f32 v[56:57], v[56:57], v[62:63]
	v_pk_add_f32 v[62:63], v[54:55], v[98:99]
	v_pk_add_f32 v[54:55], v[52:53], v[66:67]
	v_mul_f32_e32 v52, v57, v57
	v_mul_f32_e32 v53, v59, v59
	v_fmac_f32_e32 v52, v56, v56
	v_fmac_f32_e32 v53, v58, v58
	v_add_f32_e32 v52, v52, v53
	v_mul_f32_e32 v53, v55, v55
	v_fmac_f32_e32 v53, v54, v54
	v_add_f32_e32 v52, v53, v52
	v_mul_f32_e32 v53, v63, v63
	v_fmac_f32_e32 v53, v62, v62
	v_add_f32_e32 v52, v53, v52
	v_add_f32_e32 v64, v100, v52
	v_cvt_pk_bf16_f32 v52, v56, v57
	v_cvt_pk_bf16_f32 v53, v58, v59
	v_cvt_pk_bf16_f32 v54, v54, v55
	v_cvt_pk_bf16_f32 v55, v62, v63
	global_store_dwordx4 v[60:61], v[52:55], off offset:256
	ds_bpermute_b32 v52, v195, v64
	s_waitcnt lgkmcnt(0)
	v_add_f32_e32 v52, v64, v52
	ds_bpermute_b32 v53, v180, v52
	s_and_saveexec_b64 s[44:45], s[6:7]
	s_cbranch_execz .LBB0_347
	s_waitcnt lgkmcnt(0)
	v_add_f32_e32 v52, v52, v53
	ds_write_b32 v193, v52 offset:2048
.LBB0_347:
	s_or_b64 exec, exec, s[44:45]
	v_lshlrev_b32_e32 v52, 16, v88
	s_waitcnt lgkmcnt(0)
	v_and_b32_e32 v53, 0xffff0000, v88
	v_lshlrev_b32_e32 v54, 16, v89
	v_and_b32_e32 v55, 0xffff0000, v89
	v_lshlrev_b32_e32 v56, 16, v90
	v_and_b32_e32 v57, 0xffff0000, v90
	v_lshlrev_b32_e32 v58, 16, v91
	v_and_b32_e32 v59, 0xffff0000, v91
	v_pk_add_f32 v[50:51], v[50:51], v[54:55]
	v_pk_add_f32 v[48:49], v[48:49], v[52:53]
	v_pk_add_f32 v[52:53], v[46:47], v[58:59]
	v_pk_add_f32 v[46:47], v[44:45], v[56:57]
	v_mul_f32_e32 v44, v49, v49
	v_mul_f32_e32 v45, v51, v51
	v_fmac_f32_e32 v44, v48, v48
	v_fmac_f32_e32 v45, v50, v50
	v_add_f32_e32 v44, v44, v45
	v_mul_f32_e32 v45, v47, v47
	v_fmac_f32_e32 v45, v46, v46
	v_add_f32_e32 v44, v45, v44
	v_mul_f32_e32 v45, v53, v53
	v_fmac_f32_e32 v45, v52, v52
	v_add_f32_e32 v56, v45, v44
	v_cvt_pk_bf16_f32 v44, v48, v49
	v_cvt_pk_bf16_f32 v45, v50, v51
	v_lshlrev_b32_e32 v48, 16, v84
	v_and_b32_e32 v49, 0xffff0000, v84
	v_lshlrev_b32_e32 v50, 16, v85
	v_and_b32_e32 v51, 0xffff0000, v85
	v_cvt_pk_bf16_f32 v46, v46, v47
	v_cvt_pk_bf16_f32 v47, v52, v53
	v_lshlrev_b32_e32 v52, 16, v86
	v_and_b32_e32 v53, 0xffff0000, v86
	v_pk_add_f32 v[42:43], v[42:43], v[50:51]
	v_pk_add_f32 v[40:41], v[40:41], v[48:49]
	v_pk_add_f32 v[50:51], v[36:37], v[52:53]
	v_mul_f32_e32 v36, v41, v41
	v_mul_f32_e32 v37, v43, v43
	v_fmac_f32_e32 v36, v40, v40
	v_fmac_f32_e32 v37, v42, v42
	v_lshlrev_b32_e32 v54, 16, v87
	v_and_b32_e32 v55, 0xffff0000, v87
	v_add_f32_e32 v36, v36, v37
	v_mul_f32_e32 v37, v51, v51
	v_pk_add_f32 v[48:49], v[38:39], v[54:55]
	v_fmac_f32_e32 v37, v50, v50
	v_add_f32_e32 v36, v37, v36
	v_mul_f32_e32 v37, v49, v49
	v_fmac_f32_e32 v37, v48, v48
	v_add_f32_e32 v36, v37, v36
	v_add_f32_e32 v39, v56, v36
	ds_bpermute_b32 v54, v195, v39
	v_lshl_add_u64 v[36:37], s[42:43], 0, v[96:97]
	v_lshl_add_u64 v[52:53], v[170:171], 1, v[36:37]
	v_cvt_pk_bf16_f32 v38, v40, v41
	v_cvt_pk_bf16_f32 v40, v50, v51
	s_waitcnt lgkmcnt(0)
	v_add_f32_e32 v36, v39, v54
	ds_bpermute_b32 v37, v180, v36
	v_cvt_pk_bf16_f32 v39, v42, v43
	v_cvt_pk_bf16_f32 v41, v48, v49
	global_store_dwordx4 v[52:53], v[44:47], off
	global_store_dwordx4 v[52:53], v[38:41], off offset:256
	s_and_saveexec_b64 s[44:45], s[6:7]
	s_cbranch_execz .LBB0_349
	s_waitcnt lgkmcnt(0)
	v_add_f32_e32 v36, v36, v37
	ds_write_b32 v193, v36 offset:2304
.LBB0_349:
	s_or_b64 exec, exec, s[44:45]
	v_lshlrev_b32_e32 v36, 16, v80
	s_waitcnt lgkmcnt(0)
	v_and_b32_e32 v37, 0xffff0000, v80
	v_lshlrev_b32_e32 v38, 16, v81
	v_and_b32_e32 v39, 0xffff0000, v81
	v_lshlrev_b32_e32 v40, 16, v82
	v_and_b32_e32 v41, 0xffff0000, v82
	v_lshlrev_b32_e32 v42, 16, v83
	v_and_b32_e32 v43, 0xffff0000, v83
	v_pk_add_f32 v[34:35], v[34:35], v[38:39]
	v_pk_add_f32 v[32:33], v[32:33], v[36:37]
	v_pk_add_f32 v[36:37], v[30:31], v[42:43]
	v_pk_add_f32 v[30:31], v[28:29], v[40:41]
	v_mul_f32_e32 v28, v33, v33
	v_mul_f32_e32 v29, v35, v35
	v_fmac_f32_e32 v28, v32, v32
	v_fmac_f32_e32 v29, v34, v34
	v_add_f32_e32 v28, v28, v29
	v_mul_f32_e32 v29, v31, v31
	v_fmac_f32_e32 v29, v30, v30
	v_add_f32_e32 v28, v29, v28
	v_mul_f32_e32 v29, v37, v37
	v_fmac_f32_e32 v29, v36, v36
	v_add_f32_e32 v40, v29, v28
	v_cvt_pk_bf16_f32 v28, v32, v33
	v_cvt_pk_bf16_f32 v29, v34, v35
	v_lshlrev_b32_e32 v32, 16, v76
	v_and_b32_e32 v33, 0xffff0000, v76
	v_lshlrev_b32_e32 v34, 16, v77
	v_and_b32_e32 v35, 0xffff0000, v77
	v_cvt_pk_bf16_f32 v30, v30, v31
	v_cvt_pk_bf16_f32 v31, v36, v37
	v_lshlrev_b32_e32 v36, 16, v78
	v_and_b32_e32 v37, 0xffff0000, v78
	v_pk_add_f32 v[26:27], v[26:27], v[34:35]
	v_pk_add_f32 v[24:25], v[24:25], v[32:33]
	v_pk_add_f32 v[34:35], v[20:21], v[36:37]
	v_mul_f32_e32 v20, v25, v25
	v_mul_f32_e32 v21, v27, v27
	v_fmac_f32_e32 v20, v24, v24
	v_fmac_f32_e32 v21, v26, v26
	v_lshlrev_b32_e32 v38, 16, v79
	v_and_b32_e32 v39, 0xffff0000, v79
	v_add_f32_e32 v20, v20, v21
	v_mul_f32_e32 v21, v35, v35
	v_pk_add_f32 v[32:33], v[22:23], v[38:39]
	v_fmac_f32_e32 v21, v34, v34
	v_add_f32_e32 v20, v21, v20
	v_mul_f32_e32 v21, v33, v33
	v_fmac_f32_e32 v21, v32, v32
	v_add_f32_e32 v20, v21, v20
	v_add_f32_e32 v23, v40, v20
	ds_bpermute_b32 v38, v195, v23
	v_lshl_add_u64 v[20:21], s[42:43], 0, v[94:95]
	v_lshl_add_u64 v[36:37], v[170:171], 1, v[20:21]
	v_cvt_pk_bf16_f32 v22, v24, v25
	v_cvt_pk_bf16_f32 v24, v34, v35
	s_waitcnt lgkmcnt(0)
	v_add_f32_e32 v20, v23, v38
	ds_bpermute_b32 v21, v180, v20
	v_cvt_pk_bf16_f32 v23, v26, v27
	v_cvt_pk_bf16_f32 v25, v32, v33
	global_store_dwordx4 v[36:37], v[28:31], off
	global_store_dwordx4 v[36:37], v[22:25], off offset:256
	s_and_saveexec_b64 s[44:45], s[6:7]
	s_cbranch_execz .LBB0_351
	s_waitcnt lgkmcnt(0)
	v_add_f32_e32 v20, v20, v21
	ds_write_b32 v193, v20 offset:2560
.LBB0_351:
	s_or_b64 exec, exec, s[44:45]
	v_lshlrev_b32_e32 v20, 16, v72
	s_waitcnt lgkmcnt(0)
	v_and_b32_e32 v21, 0xffff0000, v72
	v_lshlrev_b32_e32 v22, 16, v73
	v_and_b32_e32 v23, 0xffff0000, v73
	v_lshlrev_b32_e32 v24, 16, v74
	v_and_b32_e32 v25, 0xffff0000, v74
	v_lshlrev_b32_e32 v26, 16, v75
	v_and_b32_e32 v27, 0xffff0000, v75
	v_pk_add_f32 v[18:19], v[18:19], v[22:23]
	v_pk_add_f32 v[16:17], v[16:17], v[20:21]
	v_pk_add_f32 v[20:21], v[14:15], v[26:27]
	v_pk_add_f32 v[14:15], v[12:13], v[24:25]
	v_mul_f32_e32 v12, v17, v17
	v_mul_f32_e32 v13, v19, v19
	v_fmac_f32_e32 v12, v16, v16
	v_fmac_f32_e32 v13, v18, v18
	v_add_f32_e32 v12, v12, v13
	v_mul_f32_e32 v13, v15, v15
	v_fmac_f32_e32 v13, v14, v14
	v_add_f32_e32 v12, v13, v12
	v_mul_f32_e32 v13, v21, v21
	v_fmac_f32_e32 v13, v20, v20
	v_add_f32_e32 v24, v13, v12
	v_cvt_pk_bf16_f32 v12, v16, v17
	v_cvt_pk_bf16_f32 v13, v18, v19
	v_lshlrev_b32_e32 v16, 16, v68
	v_and_b32_e32 v17, 0xffff0000, v68
	v_lshlrev_b32_e32 v18, 16, v69
	v_and_b32_e32 v19, 0xffff0000, v69
	v_cvt_pk_bf16_f32 v14, v14, v15
	v_cvt_pk_bf16_f32 v15, v20, v21
	v_lshlrev_b32_e32 v20, 16, v70
	v_and_b32_e32 v21, 0xffff0000, v70
	v_pk_add_f32 v[10:11], v[10:11], v[18:19]
	v_pk_add_f32 v[8:9], v[8:9], v[16:17]
	v_pk_add_f32 v[18:19], v[4:5], v[20:21]
	v_mul_f32_e32 v4, v9, v9
	v_mul_f32_e32 v5, v11, v11
	v_fmac_f32_e32 v4, v8, v8
	v_fmac_f32_e32 v5, v10, v10
	v_lshlrev_b32_e32 v22, 16, v71
	v_and_b32_e32 v23, 0xffff0000, v71
	v_add_f32_e32 v4, v4, v5
	v_mul_f32_e32 v5, v19, v19
	v_pk_add_f32 v[16:17], v[6:7], v[22:23]
	v_fmac_f32_e32 v5, v18, v18
	v_add_f32_e32 v4, v5, v4
	v_mul_f32_e32 v5, v17, v17
	v_fmac_f32_e32 v5, v16, v16
	v_add_f32_e32 v4, v5, v4
	v_add_f32_e32 v7, v24, v4
	ds_bpermute_b32 v22, v195, v7
	v_lshl_add_u64 v[4:5], s[42:43], 0, v[92:93]
	v_lshl_add_u64 v[20:21], v[170:171], 1, v[4:5]
	v_cvt_pk_bf16_f32 v6, v8, v9
	v_cvt_pk_bf16_f32 v8, v18, v19
	s_waitcnt lgkmcnt(0)
	v_add_f32_e32 v4, v7, v22
	ds_bpermute_b32 v5, v180, v4
	v_cvt_pk_bf16_f32 v7, v10, v11
	v_cvt_pk_bf16_f32 v9, v16, v17
	global_store_dwordx4 v[20:21], v[12:15], off
	global_store_dwordx4 v[20:21], v[6:9], off offset:256
	s_and_saveexec_b64 s[44:45], s[6:7]
	s_cbranch_execz .LBB0_353
	s_waitcnt lgkmcnt(0)
	v_add_f32_e32 v4, v4, v5
	ds_write_b32 v193, v4 offset:2816

.LBB0_627:
	v_and_b32_e32 v133, 64, v216
	v_xor_b32_e32 v132, 16, v216
	v_add_u32_e32 v133, 64, v133
	v_cmp_lt_i32_e32 vcc, v132, v133
	s_lshl_b32 s27, s27, 8
	v_lshl_or_b32 v170, s26, 8, v192
	v_cndmask_b32_e32 v132, v216, v132, vcc
	v_add_u32_e32 v172, s27, v3
	v_ashrrev_i32_e32 v171, 31, v170
	v_lshlrev_b32_e32 v195, 2, v132
	v_xor_b32_e32 v132, 32, v216
	v_cmp_lt_i32_e32 vcc, v132, v133
	v_lshlrev_b64 v[182:183], 1, v[170:171]
	v_ashrrev_i32_e32 v173, 31, v172
	v_cndmask_b32_e32 v132, v216, v132, vcc
	v_lshl_add_u64 v[174:175], s[42:43], 0, v[182:183]
	v_lshlrev_b64 v[184:185], 11, v[172:173]
	v_lshlrev_b32_e32 v180, 2, v132
	v_lshl_add_u64 v[132:133], v[174:175], 0, v[184:185]
	global_load_dwordx4 v[196:199], v[132:133], off
	global_load_dwordx4 v[156:159], v[132:133], off offset:256
	v_or_b32_e32 v132, 16, v172
	v_ashrrev_i32_e32 v133, 31, v132
	v_lshlrev_b64 v[190:191], 11, v[132:133]
	v_lshl_add_u64 v[132:133], v[174:175], 0, v[190:191]
	global_load_dwordx4 v[152:155], v[132:133], off
	global_load_dwordx4 v[148:151], v[132:133], off offset:256
	v_or_b32_e32 v132, 32, v172
	v_ashrrev_i32_e32 v133, 31, v132
	v_lshlrev_b64 v[178:179], 11, v[132:133]
	v_lshl_add_u64 v[132:133], v[174:175], 0, v[178:179]
	global_load_dwordx4 v[144:147], v[132:133], off
	global_load_dwordx4 v[140:143], v[132:133], off offset:256
	v_or_b32_e32 v132, 48, v172
	v_ashrrev_i32_e32 v133, 31, v132
	v_lshlrev_b64 v[176:177], 11, v[132:133]
	v_lshl_add_u64 v[132:133], v[174:175], 0, v[176:177]
	global_load_dwordx4 v[136:139], v[132:133], off
	s_nop 0
	global_load_dwordx4 v[132:135], v[132:133], off offset:256
	v_lshlrev_b64 v[160:161], 11, v[172:173]
	v_lshl_add_u64 v[160:161], v[174:175], 0, v[160:161]
	s_mov_b64 s[100:101], 0x40000
	v_lshl_add_u64 v[162:163], v[160:161], 0, s[100:101]
	global_load_dwordx4 v[204:207], v[162:163], off
	global_load_dwordx4 v[208:211], v[162:163], off offset:256
	s_mov_b64 s[100:101], 0x48000
	v_lshl_add_u64 v[162:163], v[160:161], 0, s[100:101]
	global_load_dwordx4 v[224:227], v[162:163], off
	global_load_dwordx4 v[228:231], v[162:163], off offset:256
	s_mov_b64 s[100:101], 0x50000
	v_lshl_add_u64 v[162:163], v[160:161], 0, s[100:101]
	global_load_dwordx4 v[232:235], v[162:163], off
	global_load_dwordx4 v[236:239], v[162:163], off offset:256
	s_mov_b64 s[100:101], 0x58000
	v_lshl_add_u64 v[162:163], v[160:161], 0, s[100:101]
	global_load_dwordx4 v[240:243], v[162:163], off
	global_load_dwordx4 v[218:221], v[162:163], off offset:256
	s_waitcnt vmcnt(8)
	v_lshlrev_b32_e32 v200, 16, v196
	v_and_b32_e32 v201, 0xffff0000, v196
	v_lshlrev_b32_e32 v196, 16, v197
	v_and_b32_e32 v197, 0xffff0000, v197
	v_lshlrev_b32_e32 v202, 16, v198
	v_and_b32_e32 v203, 0xffff0000, v198
	v_lshlrev_b32_e32 v198, 16, v199
	v_and_b32_e32 v199, 0xffff0000, v199
	v_pk_fma_f32 v[130:131], v[130:131], 0.5, v[196:197] op_sel_hi:[1,0,1]
	v_pk_fma_f32 v[128:129], v[128:129], 0.5, v[200:201] op_sel_hi:[1,0,1]
	v_pk_fma_f32 v[196:197], v[126:127], 0.5, v[198:199] op_sel_hi:[1,0,1]
	v_mul_f32_e32 v126, v129, v129
	v_mul_f32_e32 v127, v131, v131
	v_pk_fma_f32 v[124:125], v[124:125], 0.5, v[202:203] op_sel_hi:[1,0,1]
	v_fmac_f32_e32 v126, v128, v128
	v_fmac_f32_e32 v127, v130, v130
	v_add_f32_e32 v126, v126, v127
	v_mul_f32_e32 v127, v125, v125
	v_fmac_f32_e32 v127, v124, v124
	v_add_f32_e32 v126, v127, v126
	v_mul_f32_e32 v127, v197, v197
	v_fmac_f32_e32 v127, v196, v196
	v_add_f32_e32 v198, v127, v126
	v_cvt_pk_bf16_f32 v126, v128, v129
	v_cvt_pk_bf16_f32 v128, v124, v125
	v_lshl_add_u64 v[124:125], s[42:43], 0, v[184:185]
	v_cvt_pk_bf16_f32 v127, v130, v131
	v_cvt_pk_bf16_f32 v129, v196, v197
	v_lshl_add_u64 v[124:125], v[124:125], 0, v[182:183]
	global_store_dwordx4 v[124:125], v[126:129], off
	v_lshlrev_b32_e32 v130, 16, v158
	v_and_b32_e32 v131, 0xffff0000, v158
	v_lshlrev_b32_e32 v126, 16, v156
	v_and_b32_e32 v127, 0xffff0000, v156
	v_lshlrev_b32_e32 v128, 16, v157
	v_and_b32_e32 v129, 0xffff0000, v157
	v_lshlrev_b32_e32 v156, 16, v159
	v_and_b32_e32 v157, 0xffff0000, v159
	v_pk_fma_f32 v[122:123], v[122:123], 0.5, v[128:129] op_sel_hi:[1,0,1]
	v_pk_fma_f32 v[120:121], v[120:121], 0.5, v[126:127] op_sel_hi:[1,0,1]
	v_pk_fma_f32 v[126:127], v[118:119], 0.5, v[156:157] op_sel_hi:[1,0,1]
	v_pk_fma_f32 v[118:119], v[116:117], 0.5, v[130:131] op_sel_hi:[1,0,1]
	v_mul_f32_e32 v116, v121, v121
	v_mul_f32_e32 v117, v123, v123
	v_fmac_f32_e32 v116, v120, v120
	v_fmac_f32_e32 v117, v122, v122
	v_add_f32_e32 v116, v116, v117
	v_mul_f32_e32 v117, v119, v119
	v_fmac_f32_e32 v117, v118, v118
	v_add_f32_e32 v116, v117, v116
	v_mul_f32_e32 v117, v127, v127
	v_fmac_f32_e32 v117, v126, v126
	v_add_f32_e32 v116, v117, v116
	v_add_f32_e32 v128, v198, v116
	v_cvt_pk_bf16_f32 v116, v120, v121
	v_cvt_pk_bf16_f32 v117, v122, v123
	v_cvt_pk_bf16_f32 v118, v118, v119
	v_cvt_pk_bf16_f32 v119, v126, v127
	global_store_dwordx4 v[124:125], v[116:119], off offset:256
	ds_bpermute_b32 v116, v195, v128
	s_waitcnt lgkmcnt(0)
	v_add_f32_e32 v116, v128, v116
	ds_bpermute_b32 v117, v180, v116
	s_and_saveexec_b64 s[44:45], s[8:9]
	s_cbranch_execz .LBB0_629
	s_waitcnt lgkmcnt(0)
	v_add_f32_e32 v116, v116, v117
	ds_write_b32 v193, v116

.LBB0_635:
	s_or_b64 exec, exec, s[44:45]
	s_waitcnt lgkmcnt(0)
	v_lshlrev_b64 v[68:69], 11, v[172:173]
	s_mov_b64 s[40:41], 0x40000
	v_lshl_add_u64 v[106:107], v[68:69], 0, s[40:41]
	v_lshl_add_u64 v[70:71], v[174:175], 0, v[106:107]
	s_mov_b64 s[40:41], 0x48000
	v_lshl_add_u64 v[96:97], v[68:69], 0, s[40:41]
	s_mov_b64 s[40:41], 0x50000
	v_lshl_add_u64 v[94:95], v[68:69], 0, s[40:41]
	s_mov_b64 s[40:41], 0x58000
	v_lshl_add_u64 v[70:71], v[174:175], 0, v[96:97]
	v_lshl_add_u64 v[92:93], v[68:69], 0, s[40:41]
	v_lshl_add_u64 v[70:71], v[174:175], 0, v[94:95]
	v_lshl_add_u64 v[68:69], v[174:175], 0, v[92:93]
	s_waitcnt vmcnt(8)
	v_mov_b32_e32 v98, v204
	v_mov_b32_e32 v99, v205
	v_mov_b32_e32 v100, v206
	v_mov_b32_e32 v101, v207
	v_mov_b32_e32 v102, v208
	v_mov_b32_e32 v103, v209
	v_mov_b32_e32 v104, v210
	v_mov_b32_e32 v105, v211
	v_mov_b32_e32 v88, v224
	v_mov_b32_e32 v89, v225
	v_mov_b32_e32 v90, v226
	v_mov_b32_e32 v91, v227
	v_mov_b32_e32 v84, v228
	v_mov_b32_e32 v85, v229
	v_mov_b32_e32 v86, v230
	v_mov_b32_e32 v87, v231
	v_mov_b32_e32 v80, v232
	v_mov_b32_e32 v81, v233
	v_mov_b32_e32 v82, v234
	v_mov_b32_e32 v83, v235
	v_mov_b32_e32 v76, v236
	v_mov_b32_e32 v77, v237
	v_mov_b32_e32 v78, v238
	v_mov_b32_e32 v79, v239
	v_mov_b32_e32 v72, v240
	v_mov_b32_e32 v73, v241
	v_mov_b32_e32 v74, v242
	v_mov_b32_e32 v75, v243
	v_mov_b32_e32 v68, v218
	v_mov_b32_e32 v69, v219
	v_mov_b32_e32 v70, v220
	v_mov_b32_e32 v71, v221
	v_lshlrev_b32_e32 v108, 16, v98
	v_and_b32_e32 v109, 0xffff0000, v98
	v_lshlrev_b32_e32 v98, 16, v99
	v_and_b32_e32 v99, 0xffff0000, v99
	v_lshlrev_b32_e32 v110, 16, v100
	v_and_b32_e32 v111, 0xffff0000, v100
	v_lshlrev_b32_e32 v100, 16, v101
	v_and_b32_e32 v101, 0xffff0000, v101
	v_pk_fma_f32 v[66:67], v[66:67], 0.5, v[98:99] op_sel_hi:[1,0,1]
	v_pk_fma_f32 v[64:65], v[64:65], 0.5, v[108:109] op_sel_hi:[1,0,1]
	v_pk_fma_f32 v[98:99], v[62:63], 0.5, v[100:101] op_sel_hi:[1,0,1]
	v_mul_f32_e32 v62, v65, v65
	v_mul_f32_e32 v63, v67, v67
	v_pk_fma_f32 v[60:61], v[60:61], 0.5, v[110:111] op_sel_hi:[1,0,1]
	v_fmac_f32_e32 v62, v64, v64
	v_fmac_f32_e32 v63, v66, v66
	v_add_f32_e32 v62, v62, v63
	v_mul_f32_e32 v63, v61, v61
	v_fmac_f32_e32 v63, v60, v60
	v_add_f32_e32 v62, v63, v62
	v_mul_f32_e32 v63, v99, v99
	v_fmac_f32_e32 v63, v98, v98
	v_add_f32_e32 v100, v63, v62
	v_cvt_pk_bf16_f32 v62, v64, v65
	v_cvt_pk_bf16_f32 v64, v60, v61
	v_lshl_add_u64 v[60:61], s[42:43], 0, v[106:107]
	v_cvt_pk_bf16_f32 v63, v66, v67
	v_cvt_pk_bf16_f32 v65, v98, v99
	v_lshl_add_u64 v[60:61], v[170:171], 1, v[60:61]
	global_store_dwordx4 v[60:61], v[62:65], off
	v_lshlrev_b32_e32 v66, 16, v104
	v_and_b32_e32 v67, 0xffff0000, v104
	v_lshlrev_b32_e32 v62, 16, v102
	v_and_b32_e32 v63, 0xffff0000, v102
	v_lshlrev_b32_e32 v64, 16, v103
	v_and_b32_e32 v65, 0xffff0000, v103
	v_lshlrev_b32_e32 v98, 16, v105
	v_and_b32_e32 v99, 0xffff0000, v105
	v_pk_fma_f32 v[58:59], v[58:59], 0.5, v[64:65] op_sel_hi:[1,0,1]
	v_pk_fma_f32 v[56:57], v[56:57], 0.5, v[62:63] op_sel_hi:[1,0,1]
	v_pk_fma_f32 v[62:63], v[54:55], 0.5, v[98:99] op_sel_hi:[1,0,1]
	v_pk_fma_f32 v[54:55], v[52:53], 0.5, v[66:67] op_sel_hi:[1,0,1]
	v_mul_f32_e32 v52, v57, v57
	v_mul_f32_e32 v53, v59, v59
	v_fmac_f32_e32 v52, v56, v56
	v_fmac_f32_e32 v53, v58, v58
	v_add_f32_e32 v52, v52, v53
	v_mul_f32_e32 v53, v55, v55
	v_fmac_f32_e32 v53, v54, v54
	v_add_f32_e32 v52, v53, v52
	v_mul_f32_e32 v53, v63, v63
	v_fmac_f32_e32 v53, v62, v62
	v_add_f32_e32 v52, v53, v52
	v_add_f32_e32 v64, v100, v52
	v_cvt_pk_bf16_f32 v52, v56, v57
	v_cvt_pk_bf16_f32 v53, v58, v59
	v_cvt_pk_bf16_f32 v54, v54, v55
	v_cvt_pk_bf16_f32 v55, v62, v63
	global_store_dwordx4 v[60:61], v[52:55], off offset:256
	ds_bpermute_b32 v52, v195, v64
	s_waitcnt lgkmcnt(0)
	v_add_f32_e32 v52, v64, v52
	ds_bpermute_b32 v53, v180, v52
	s_and_saveexec_b64 s[44:45], s[8:9]
	s_cbranch_execz .LBB0_637
	s_waitcnt lgkmcnt(0)
	v_add_f32_e32 v52, v52, v53
	ds_write_b32 v193, v52 offset:2048
.LBB0_637:
	s_or_b64 exec, exec, s[44:45]
	v_lshlrev_b32_e32 v52, 16, v88
	s_waitcnt lgkmcnt(0)
	v_and_b32_e32 v53, 0xffff0000, v88
	v_lshlrev_b32_e32 v54, 16, v89
	v_and_b32_e32 v55, 0xffff0000, v89
	v_lshlrev_b32_e32 v56, 16, v90
	v_and_b32_e32 v57, 0xffff0000, v90
	v_lshlrev_b32_e32 v58, 16, v91
	v_and_b32_e32 v59, 0xffff0000, v91
	v_pk_fma_f32 v[50:51], v[50:51], 0.5, v[54:55] op_sel_hi:[1,0,1]
	v_pk_fma_f32 v[48:49], v[48:49], 0.5, v[52:53] op_sel_hi:[1,0,1]
	v_pk_fma_f32 v[52:53], v[46:47], 0.5, v[58:59] op_sel_hi:[1,0,1]
	v_pk_fma_f32 v[46:47], v[44:45], 0.5, v[56:57] op_sel_hi:[1,0,1]
	v_mul_f32_e32 v44, v49, v49
	v_mul_f32_e32 v45, v51, v51
	v_fmac_f32_e32 v44, v48, v48
	v_fmac_f32_e32 v45, v50, v50
	v_add_f32_e32 v44, v44, v45
	v_mul_f32_e32 v45, v47, v47
	v_fmac_f32_e32 v45, v46, v46
	v_add_f32_e32 v44, v45, v44
	v_mul_f32_e32 v45, v53, v53
	v_fmac_f32_e32 v45, v52, v52
	v_add_f32_e32 v56, v45, v44
	v_cvt_pk_bf16_f32 v44, v48, v49
	v_cvt_pk_bf16_f32 v45, v50, v51
	v_lshlrev_b32_e32 v48, 16, v84
	v_and_b32_e32 v49, 0xffff0000, v84
	v_lshlrev_b32_e32 v50, 16, v85
	v_and_b32_e32 v51, 0xffff0000, v85
	v_cvt_pk_bf16_f32 v46, v46, v47
	v_cvt_pk_bf16_f32 v47, v52, v53
	v_lshlrev_b32_e32 v52, 16, v86
	v_and_b32_e32 v53, 0xffff0000, v86
	v_pk_fma_f32 v[42:43], v[42:43], 0.5, v[50:51] op_sel_hi:[1,0,1]
	v_pk_fma_f32 v[40:41], v[40:41], 0.5, v[48:49] op_sel_hi:[1,0,1]
	v_pk_fma_f32 v[50:51], v[36:37], 0.5, v[52:53] op_sel_hi:[1,0,1]
	v_mul_f32_e32 v36, v41, v41
	v_mul_f32_e32 v37, v43, v43
	v_fmac_f32_e32 v36, v40, v40
	v_fmac_f32_e32 v37, v42, v42
	v_lshlrev_b32_e32 v54, 16, v87
	v_and_b32_e32 v55, 0xffff0000, v87
	v_add_f32_e32 v36, v36, v37
	v_mul_f32_e32 v37, v51, v51
	v_pk_fma_f32 v[48:49], v[38:39], 0.5, v[54:55] op_sel_hi:[1,0,1]
	v_fmac_f32_e32 v37, v50, v50
	v_add_f32_e32 v36, v37, v36
	v_mul_f32_e32 v37, v49, v49
	v_fmac_f32_e32 v37, v48, v48
	v_add_f32_e32 v36, v37, v36
	v_add_f32_e32 v39, v56, v36
	ds_bpermute_b32 v54, v195, v39
	v_lshl_add_u64 v[36:37], s[42:43], 0, v[96:97]
	v_lshl_add_u64 v[52:53], v[170:171], 1, v[36:37]
	v_cvt_pk_bf16_f32 v38, v40, v41
	v_cvt_pk_bf16_f32 v40, v50, v51
	s_waitcnt lgkmcnt(0)
	v_add_f32_e32 v36, v39, v54
	ds_bpermute_b32 v37, v180, v36
	v_cvt_pk_bf16_f32 v39, v42, v43
	v_cvt_pk_bf16_f32 v41, v48, v49
	global_store_dwordx4 v[52:53], v[44:47], off
	global_store_dwordx4 v[52:53], v[38:41], off offset:256
	s_and_saveexec_b64 s[44:45], s[8:9]
	s_cbranch_execz .LBB0_639
	s_waitcnt lgkmcnt(0)
	v_add_f32_e32 v36, v36, v37
	ds_write_b32 v193, v36 offset:2304
.LBB0_639:
	s_or_b64 exec, exec, s[44:45]
	v_lshlrev_b32_e32 v36, 16, v80
	s_waitcnt lgkmcnt(0)
	v_and_b32_e32 v37, 0xffff0000, v80
	v_lshlrev_b32_e32 v38, 16, v81
	v_and_b32_e32 v39, 0xffff0000, v81
	v_lshlrev_b32_e32 v40, 16, v82
	v_and_b32_e32 v41, 0xffff0000, v82
	v_lshlrev_b32_e32 v42, 16, v83
	v_and_b32_e32 v43, 0xffff0000, v83
	v_pk_fma_f32 v[34:35], v[34:35], 0.5, v[38:39] op_sel_hi:[1,0,1]
	v_pk_fma_f32 v[32:33], v[32:33], 0.5, v[36:37] op_sel_hi:[1,0,1]
	v_pk_fma_f32 v[36:37], v[30:31], 0.5, v[42:43] op_sel_hi:[1,0,1]
	v_pk_fma_f32 v[30:31], v[28:29], 0.5, v[40:41] op_sel_hi:[1,0,1]
	v_mul_f32_e32 v28, v33, v33
	v_mul_f32_e32 v29, v35, v35
	v_fmac_f32_e32 v28, v32, v32
	v_fmac_f32_e32 v29, v34, v34
	v_add_f32_e32 v28, v28, v29
	v_mul_f32_e32 v29, v31, v31
	v_fmac_f32_e32 v29, v30, v30
	v_add_f32_e32 v28, v29, v28
	v_mul_f32_e32 v29, v37, v37
	v_fmac_f32_e32 v29, v36, v36
	v_add_f32_e32 v40, v29, v28
	v_cvt_pk_bf16_f32 v28, v32, v33
	v_cvt_pk_bf16_f32 v29, v34, v35
	v_lshlrev_b32_e32 v32, 16, v76
	v_and_b32_e32 v33, 0xffff0000, v76
	v_lshlrev_b32_e32 v34, 16, v77
	v_and_b32_e32 v35, 0xffff0000, v77
	v_cvt_pk_bf16_f32 v30, v30, v31
	v_cvt_pk_bf16_f32 v31, v36, v37
	v_lshlrev_b32_e32 v36, 16, v78
	v_and_b32_e32 v37, 0xffff0000, v78
	v_pk_fma_f32 v[26:27], v[26:27], 0.5, v[34:35] op_sel_hi:[1,0,1]
	v_pk_fma_f32 v[24:25], v[24:25], 0.5, v[32:33] op_sel_hi:[1,0,1]
	v_pk_fma_f32 v[34:35], v[20:21], 0.5, v[36:37] op_sel_hi:[1,0,1]
	v_mul_f32_e32 v20, v25, v25
	v_mul_f32_e32 v21, v27, v27
	v_fmac_f32_e32 v20, v24, v24
	v_fmac_f32_e32 v21, v26, v26
	v_lshlrev_b32_e32 v38, 16, v79
	v_and_b32_e32 v39, 0xffff0000, v79
	v_add_f32_e32 v20, v20, v21
	v_mul_f32_e32 v21, v35, v35
	v_pk_fma_f32 v[32:33], v[22:23], 0.5, v[38:39] op_sel_hi:[1,0,1]
	v_fmac_f32_e32 v21, v34, v34
	v_add_f32_e32 v20, v21, v20
	v_mul_f32_e32 v21, v33, v33
	v_fmac_f32_e32 v21, v32, v32
	v_add_f32_e32 v20, v21, v20
	v_add_f32_e32 v23, v40, v20
	ds_bpermute_b32 v38, v195, v23
	v_lshl_add_u64 v[20:21], s[42:43], 0, v[94:95]
	v_lshl_add_u64 v[36:37], v[170:171], 1, v[20:21]
	v_cvt_pk_bf16_f32 v22, v24, v25
	v_cvt_pk_bf16_f32 v24, v34, v35
	s_waitcnt lgkmcnt(0)
	v_add_f32_e32 v20, v23, v38
	ds_bpermute_b32 v21, v180, v20
	v_cvt_pk_bf16_f32 v23, v26, v27
	v_cvt_pk_bf16_f32 v25, v32, v33
	global_store_dwordx4 v[36:37], v[28:31], off
	global_store_dwordx4 v[36:37], v[22:25], off offset:256
	s_and_saveexec_b64 s[44:45], s[8:9]
	s_cbranch_execz .LBB0_641
	s_waitcnt lgkmcnt(0)
	v_add_f32_e32 v20, v20, v21
	ds_write_b32 v193, v20 offset:2560
.LBB0_641:
	s_or_b64 exec, exec, s[44:45]
	v_lshlrev_b32_e32 v20, 16, v72
	s_waitcnt lgkmcnt(0)
	v_and_b32_e32 v21, 0xffff0000, v72
	v_lshlrev_b32_e32 v22, 16, v73
	v_and_b32_e32 v23, 0xffff0000, v73
	v_lshlrev_b32_e32 v24, 16, v74
	v_and_b32_e32 v25, 0xffff0000, v74
	v_lshlrev_b32_e32 v26, 16, v75
	v_and_b32_e32 v27, 0xffff0000, v75
	v_pk_fma_f32 v[18:19], v[18:19], 0.5, v[22:23] op_sel_hi:[1,0,1]
	v_pk_fma_f32 v[16:17], v[16:17], 0.5, v[20:21] op_sel_hi:[1,0,1]
	v_pk_fma_f32 v[20:21], v[14:15], 0.5, v[26:27] op_sel_hi:[1,0,1]
	v_pk_fma_f32 v[14:15], v[12:13], 0.5, v[24:25] op_sel_hi:[1,0,1]
	v_mul_f32_e32 v12, v17, v17
	v_mul_f32_e32 v13, v19, v19
	v_fmac_f32_e32 v12, v16, v16
	v_fmac_f32_e32 v13, v18, v18
	v_add_f32_e32 v12, v12, v13
	v_mul_f32_e32 v13, v15, v15
	v_fmac_f32_e32 v13, v14, v14
	v_add_f32_e32 v12, v13, v12
	v_mul_f32_e32 v13, v21, v21
	v_fmac_f32_e32 v13, v20, v20
	v_add_f32_e32 v24, v13, v12
	v_cvt_pk_bf16_f32 v12, v16, v17
	v_cvt_pk_bf16_f32 v13, v18, v19
	v_lshlrev_b32_e32 v16, 16, v68
	v_and_b32_e32 v17, 0xffff0000, v68
	v_lshlrev_b32_e32 v18, 16, v69
	v_and_b32_e32 v19, 0xffff0000, v69
	v_cvt_pk_bf16_f32 v14, v14, v15
	v_cvt_pk_bf16_f32 v15, v20, v21
	v_lshlrev_b32_e32 v20, 16, v70
	v_and_b32_e32 v21, 0xffff0000, v70
	v_pk_fma_f32 v[10:11], v[10:11], 0.5, v[18:19] op_sel_hi:[1,0,1]
	v_pk_fma_f32 v[8:9], v[8:9], 0.5, v[16:17] op_sel_hi:[1,0,1]
	v_pk_fma_f32 v[18:19], v[4:5], 0.5, v[20:21] op_sel_hi:[1,0,1]
	v_mul_f32_e32 v4, v9, v9
	v_mul_f32_e32 v5, v11, v11
	v_fmac_f32_e32 v4, v8, v8
	v_fmac_f32_e32 v5, v10, v10
	v_lshlrev_b32_e32 v22, 16, v71
	v_and_b32_e32 v23, 0xffff0000, v71
	v_add_f32_e32 v4, v4, v5
	v_mul_f32_e32 v5, v19, v19
	v_pk_fma_f32 v[16:17], v[6:7], 0.5, v[22:23] op_sel_hi:[1,0,1]
	v_fmac_f32_e32 v5, v18, v18
	v_add_f32_e32 v4, v5, v4
	v_mul_f32_e32 v5, v17, v17
	v_fmac_f32_e32 v5, v16, v16
	v_add_f32_e32 v4, v5, v4
	v_add_f32_e32 v7, v24, v4
	ds_bpermute_b32 v22, v195, v7
	v_lshl_add_u64 v[4:5], s[42:43], 0, v[92:93]
	v_lshl_add_u64 v[20:21], v[170:171], 1, v[4:5]
	v_cvt_pk_bf16_f32 v6, v8, v9
	v_cvt_pk_bf16_f32 v8, v18, v19
	s_waitcnt lgkmcnt(0)
	v_add_f32_e32 v4, v7, v22
	ds_bpermute_b32 v5, v180, v4
	v_cvt_pk_bf16_f32 v7, v10, v11
	v_cvt_pk_bf16_f32 v9, v16, v17
	global_store_dwordx4 v[20:21], v[12:15], off
	global_store_dwordx4 v[20:21], v[6:9], off offset:256
	s_and_saveexec_b64 s[44:45], s[8:9]
	s_cbranch_execz .LBB0_643
	s_waitcnt lgkmcnt(0)
	v_add_f32_e32 v4, v4, v5
	ds_write_b32 v193, v4 offset:2816

	.amdhsa_kernel _Z10fwd_kernel4Args
		.amdhsa_group_segment_fixed_size 0
		.amdhsa_private_segment_fixed_size 0
		.amdhsa_kernarg_size 488
		.amdhsa_user_sgpr_count 2
		.amdhsa_user_sgpr_dispatch_ptr 0
		.amdhsa_user_sgpr_queue_ptr 0
		.amdhsa_user_sgpr_kernarg_segment_ptr 1
		.amdhsa_user_sgpr_dispatch_id 0
		.amdhsa_user_sgpr_kernarg_preload_length 0
		.amdhsa_user_sgpr_kernarg_preload_offset 0
		.amdhsa_user_sgpr_private_segment_size 0
		.amdhsa_uses_dynamic_stack 0
		.amdhsa_enable_private_segment 0
		.amdhsa_system_sgpr_workgroup_id_x 1
		.amdhsa_system_sgpr_workgroup_id_y 0
		.amdhsa_system_sgpr_workgroup_id_z 0
		.amdhsa_system_sgpr_workgroup_info 0
		.amdhsa_system_vgpr_workitem_id 2
		.amdhsa_next_free_vgpr 256
		.amdhsa_next_free_sgpr 102
		.amdhsa_accum_offset 256
		.amdhsa_reserve_vcc 1
		.amdhsa_float_round_mode_32 0
		.amdhsa_float_round_mode_16_64 0
		.amdhsa_float_denorm_mode_32 3
		.amdhsa_float_denorm_mode_16_64 3
		.amdhsa_dx10_clamp 1
		.amdhsa_ieee_mode 1
		.amdhsa_fp16_overflow 0
		.amdhsa_tg_split 0
		.amdhsa_exception_fp_ieee_invalid_op 0
		.amdhsa_exception_fp_denorm_src 0
		.amdhsa_exception_fp_ieee_div_zero 0
		.amdhsa_exception_fp_ieee_overflow 0
		.amdhsa_exception_fp_ieee_underflow 0
		.amdhsa_exception_fp_ieee_inexact 0
		.amdhsa_exception_int_div_zero 0
	.end_amdhsa_kernel

amdhsa.kernels:
  - .agpr_count:     0
    .args:
      - .offset:         0
        .size:           232
        .value_kind:     by_value
      - .offset:         232
        .size:           4
        .value_kind:     hidden_block_count_x
      - .offset:         236
        .size:           4
        .value_kind:     hidden_block_count_y
      - .offset:         240
        .size:           4
        .value_kind:     hidden_block_count_z
      - .offset:         244
        .size:           2
        .value_kind:     hidden_group_size_x
      - .offset:         246
        .size:           2
        .value_kind:     hidden_group_size_y
      - .offset:         248
        .size:           2
        .value_kind:     hidden_group_size_z
      - .offset:         250
        .size:           2
        .value_kind:     hidden_remainder_x
      - .offset:         252
        .size:           2
        .value_kind:     hidden_remainder_y
      - .offset:         254
        .size:           2
        .value_kind:     hidden_remainder_z
      - .offset:         272
        .size:           8
        .value_kind:     hidden_global_offset_x
      - .offset:         280
        .size:           8
        .value_kind:     hidden_global_offset_y
      - .offset:         288
        .size:           8
        .value_kind:     hidden_global_offset_z
      - .offset:         296
        .size:           2
        .value_kind:     hidden_grid_dims
      - .offset:         320
        .size:           8
        .value_kind:     hidden_multigrid_sync_arg
      - .offset:         352
        .size:           4
        .value_kind:     hidden_dynamic_lds_size
    .group_segment_fixed_size: 0
    .kernarg_segment_align: 8
    .kernarg_segment_size: 488
    .language:       OpenCL C
    .language_version:
      - 2
      - 0
    .max_flat_workgroup_size: 512
    .name:           _Z10fwd_kernel4Args
    .private_segment_fixed_size: 0
    .sgpr_count:     108
    .sgpr_spill_count: 359
    .symbol:         _Z10fwd_kernel4Args.kd
    .uniform_work_group_size: 1
    .uses_dynamic_stack: false
    .vgpr_count:     256
    .vgpr_spill_count: 0
    .wavefront_size: 64
